# GEMM1 inter-unit accumulator zeroing with 64 v_mov_b64 instead of 128 v_mov_b32; on top of stage B
# speedup vs baseline: 1.0177x; 1.0033x over previous
; template <class Epi, class Sched, bool ALIGN_EPI = false, bool SP2 = true>
; DI void gemm_phase(LAS unsigned char* lds, const Gemm g, const Sched& S, const Epi& E, f32x4 (&acc)[2][2][4][2]) {
;     ...
;         const char* nA = has_next ? (const char*)g.A + (size_t)nxt.pm * tstep : cA; const char* nB = has_next ? (const char*)g.Bt + (size_t)nxt.pn * tstep : cB;
;         for (int t = 0; t < nt; t += 2) {
;             const bool last = (t == nt - 2);
;             const char* a1 = cA + (size_t)(t + 1) * kstep;
;             const char* a2 = last ? nA : cA + (size_t)(t + 2) * kstep; const char* b2 = last ? nB : cB + (size_t)(t + 2) * kstep;
;             const char* a3 = a2 + kstep; const char* b3 = b2 + kstep;
;     ...
; #pragma unroll
;         for (int a = 0; a < 2; ++a)
; #pragma unroll
;             for (int b = 0; b < 2; ++b)
; #pragma unroll
;                 for (int m = 0; m < 4; ++m)
; #pragma unroll
;                     for (int n = 0; n < 2; ++n) acc[a][b][m][n] = (f32x4){0.f, 0.f, 0.f, 0.f};
;         cur = nxt; cA = nA; cB = nB; ++ui;
.LBB0_158:
	s_ashr_i32 s25, s24, 31
	s_lshl_b64 s[26:27], s[24:25], 19
	s_add_u32 s26, s68, s26
	s_addc_u32 s27, s69, s27
	s_and_b64 s[28:29], s[20:21], exec
	s_cselect_b32 s25, s27, s1
	s_cselect_b32 s52, s26, s0
	s_ashr_i32 s23, s22, 31
	s_lshl_b64 s[28:29], s[22:23], 19
	s_add_u32 s28, s68, s28
	s_addc_u32 s29, s69, s29
	s_and_b64 s[34:35], s[20:21], exec
	s_cselect_b32 s23, s29, s31
	s_cselect_b32 s53, s28, s30
	s_add_u32 s0, s0, 0x40080
	s_addc_u32 s1, s1, 0
	s_add_u32 s54, s30, 0x100
	v_mov_b64_e32 v[0:1], 0
	v_mov_b64_e32 v[2:3], 0
	v_mov_b64_e32 v[4:5], 0
	v_mov_b64_e32 v[6:7], 0
	v_mov_b64_e32 v[8:9], 0
	v_mov_b64_e32 v[10:11], 0
	v_mov_b64_e32 v[12:13], 0
	v_mov_b64_e32 v[14:15], 0
	v_mov_b64_e32 v[16:17], 0
	v_mov_b64_e32 v[18:19], 0
	v_mov_b64_e32 v[20:21], 0
	v_mov_b64_e32 v[22:23], 0
	v_mov_b64_e32 v[24:25], 0
	v_mov_b64_e32 v[26:27], 0
	v_mov_b64_e32 v[28:29], 0
	v_mov_b64_e32 v[30:31], 0
	v_mov_b64_e32 v[32:33], 0
	v_mov_b64_e32 v[34:35], 0
	v_mov_b64_e32 v[36:37], 0
	v_mov_b64_e32 v[38:39], 0
	v_mov_b64_e32 v[40:41], 0
	v_mov_b64_e32 v[42:43], 0
	v_mov_b64_e32 v[44:45], 0
	v_mov_b64_e32 v[46:47], 0
	v_mov_b64_e32 v[48:49], 0
	v_mov_b64_e32 v[50:51], 0
	v_mov_b64_e32 v[52:53], 0
	v_mov_b64_e32 v[54:55], 0
	v_mov_b64_e32 v[56:57], 0
	v_mov_b64_e32 v[58:59], 0
	v_mov_b64_e32 v[60:61], 0
	v_mov_b64_e32 v[62:63], 0
	v_mov_b64_e32 v[64:65], 0
	v_mov_b64_e32 v[66:67], 0
	v_mov_b64_e32 v[68:69], 0
	v_mov_b64_e32 v[70:71], 0
	v_mov_b64_e32 v[72:73], 0
	v_mov_b64_e32 v[74:75], 0
	v_mov_b64_e32 v[76:77], 0
	v_mov_b64_e32 v[78:79], 0
	v_mov_b64_e32 v[80:81], 0
	v_mov_b64_e32 v[82:83], 0
	v_mov_b64_e32 v[84:85], 0
	v_mov_b64_e32 v[86:87], 0
	v_mov_b64_e32 v[88:89], 0
	v_mov_b64_e32 v[90:91], 0
	v_mov_b64_e32 v[92:93], 0
	v_mov_b64_e32 v[94:95], 0
	v_mov_b64_e32 v[96:97], 0
	v_mov_b64_e32 v[98:99], 0
	v_mov_b64_e32 v[100:101], 0
	v_mov_b64_e32 v[102:103], 0
	v_mov_b64_e32 v[104:105], 0
	v_mov_b64_e32 v[106:107], 0
	v_mov_b64_e32 v[108:109], 0
	v_mov_b64_e32 v[110:111], 0
	v_mov_b64_e32 v[112:113], 0
	v_mov_b64_e32 v[114:115], 0
	v_mov_b64_e32 v[116:117], 0
	v_mov_b64_e32 v[118:119], 0
	v_mov_b64_e32 v[120:121], 0
	v_mov_b64_e32 v[122:123], 0
	v_mov_b64_e32 v[124:125], 0
	v_mov_b64_e32 v[126:127], 0
	s_addc_u32 s55, s31, 0
	s_mov_b32 s62, -2
